# m6 plus default cache policy (not nt) for the Q, K, V outputs of the input projection, which attention consumes right after
# speedup vs baseline: 1.0316x; 1.0139x over previous
;     __device__ __forceinline__ void operator()(const pg8::f32x4 (&acc)[2][2][4][2], const pg8::Unit& u, int wr, int wc, int fr_, int fq_) const {
;     ...
;         if (vt >= 14 && vt <= 18) {
;             bf16_t* dst; int pitch, head;
;             if (vt < 18) { dst = (bf16_t*)(ws + WS_Q); pitch = DM; head = 2 * (vt - 14) + (wc >> 1); } else { dst = (bf16_t*)(ws + WS_K); pitch = DKV; head = (wc >> 1); }
;             const int dlo = 32 * (wc & 1) + 8 * fq;
;             const u32x4* rope = (const u32x4*)(ws + WS_ROPE);
; #pragma unroll
;             for (int ai = 0; ai < 2; ++ai) {
;                 u32x4 rc[4][2];
; #pragma unroll
;                 for (int m = 0; m < 4; ++m) { const int pos = (row0 + ai * HALF + m * 16) & (SEQ - 1);
;                     const u32x4* rp = rope + ((size_t)pos * 64 + dlo) / 4;
;                     rc[m][0] = rp[0]; rc[m][1] = rp[1]; }
; #pragma unroll
;                 for (int m = 0; m < 4; ++m) {
;                     const int row = row0 + ai * HALF + m * 16;
;                     const u32x4 ca = rc[m][0], cb = rc[m][1];
;                     const f32x4 t1a = acc[ai][0][m][0] * ascale + bv[0][0], t1b = acc[ai][0][m][1] * ascale + bv[0][1];
;                     const f32x4 t2a = acc[ai][1][m][0] * ascale + bv[1][0], t2b = acc[ai][1][m][1] * ascale + bv[1][1];
.LBB0_424:
	s_and_b64 vcc, exec, s[64:65]
	s_cbranch_vccz .LBB0_440
	v_mov_b64_e32 v[198:199], v[178:179]
	v_add_u32_e32 v178, s48, v162
	v_lshlrev_b32_e32 v188, 6, v174
	v_ashrrev_i32_e32 v179, 31, v178
	v_and_b32_e32 v172, 0xfffc0, v188
	v_lshl_add_u64 v[144:145], v[172:173], 0, v[178:179]
	v_lshl_add_u64 v[144:145], v[144:145], 2, s[46:47]
	global_load_dwordx4 v[168:171], v[144:145], off offset:16
	global_load_dwordx4 v[190:193], v[144:145], off
	v_add_u32_e32 v144, 0x400, v188
	v_and_b32_e32 v172, 0xfffc0, v144
	v_lshl_add_u64 v[144:145], v[172:173], 0, v[178:179]
	v_lshl_add_u64 v[144:145], v[144:145], 2, s[46:47]
	global_load_dwordx4 v[160:163], v[144:145], off offset:16
	global_load_dwordx4 v[164:167], v[144:145], off
	v_add_u32_e32 v144, 0x800, v188
	v_and_b32_e32 v172, 0xfffc0, v144
	v_lshl_add_u64 v[144:145], v[172:173], 0, v[178:179]
	v_lshl_add_u64 v[144:145], v[144:145], 2, s[46:47]
	global_load_dwordx4 v[152:155], v[144:145], off offset:16
	global_load_dwordx4 v[156:159], v[144:145], off
	v_add_u32_e32 v144, 0xc00, v188
	v_and_b32_e32 v172, 0xfffc0, v144
	v_lshl_add_u64 v[144:145], v[172:173], 0, v[178:179]
	v_lshl_add_u64 v[148:149], v[144:145], 2, s[46:47]
	global_load_dwordx4 v[144:147], v[148:149], off offset:16
	s_nop 0
	global_load_dwordx4 v[148:151], v[148:149], off
	s_cmp_lt_u32 s8, 18
	s_waitcnt vmcnt(8)
	v_pk_fma_f32 v[132:133], v[132:133], s[56:57], v[120:121] op_sel_hi:[1,0,1]
	v_pk_fma_f32 v[194:195], v[130:131], s[56:57], v[114:115] op_sel_hi:[1,0,1]
	v_pk_fma_f32 v[130:131], v[128:129], s[56:57], v[112:113] op_sel_hi:[1,0,1]
	s_cselect_b64 s[64:65], -1, 0
	s_lshl_b32 s2, s8, 1
	v_pk_fma_f32 v[140:141], v[140:141], s[56:57], v[124:125] op_sel_hi:[1,0,1]
	s_add_i32 s2, s41, s2
	s_and_b64 s[6:7], s[64:65], exec
	v_pk_fma_f32 v[134:135], v[134:135], s[56:57], v[122:123] op_sel_hi:[1,0,1]
	s_mov_b32 s6, 0xe000000
	v_pk_fma_f32 v[142:143], v[142:143], s[56:57], v[126:127] op_sel_hi:[1,0,1]
	s_cselect_b32 s6, s6, 0x12000000
	s_cselect_b32 s2, s2, s40
	s_add_u32 s6, s10, s6
	s_addc_u32 s7, s11, 0
	s_lshl_b32 s2, s2, 8
	v_pk_fma_f32 v[136:137], v[136:137], s[56:57], v[116:117] op_sel_hi:[1,0,1]
	s_add_u32 s6, s6, s2
	s_addc_u32 s7, s7, 0
	v_pk_fma_f32 v[138:139], v[138:139], s[56:57], v[118:119] op_sel_hi:[1,0,1]
	v_lshl_add_u64 v[176:177], v[178:179], 1, s[6:7]
	s_and_b64 s[6:7], s[64:65], exec
	v_ashrrev_i32_e32 v175, 31, v174
	s_cselect_b32 s8, 10, 8
	v_pk_fma_f32 v[100:101], v[100:101], s[56:57], v[120:121] op_sel_hi:[1,0,1]
	v_pk_fma_f32 v[108:109], v[108:109], s[56:57], v[124:125] op_sel_hi:[1,0,1]
	v_pk_fma_f32 v[102:103], v[102:103], s[56:57], v[122:123] op_sel_hi:[1,0,1]
	v_pk_fma_f32 v[110:111], v[110:111], s[56:57], v[126:127] op_sel_hi:[1,0,1]
	v_pk_fma_f32 v[104:105], v[104:105], s[56:57], v[116:117] op_sel_hi:[1,0,1]
	v_pk_fma_f32 v[106:107], v[106:107], s[56:57], v[118:119] op_sel_hi:[1,0,1]
	v_pk_fma_f32 v[84:85], v[84:85], s[56:57], v[120:121] op_sel_hi:[1,0,1]
	v_pk_fma_f32 v[92:93], v[92:93], s[56:57], v[124:125] op_sel_hi:[1,0,1]
	v_pk_fma_f32 v[86:87], v[86:87], s[56:57], v[122:123] op_sel_hi:[1,0,1]
	v_pk_fma_f32 v[94:95], v[94:95], s[56:57], v[126:127] op_sel_hi:[1,0,1]
	v_pk_fma_f32 v[88:89], v[88:89], s[56:57], v[116:117] op_sel_hi:[1,0,1]
	v_pk_fma_f32 v[90:91], v[90:91], s[56:57], v[118:119] op_sel_hi:[1,0,1]
	v_pk_fma_f32 v[68:69], v[68:69], s[56:57], v[120:121] op_sel_hi:[1,0,1]
	v_pk_fma_f32 v[76:77], v[76:77], s[56:57], v[124:125] op_sel_hi:[1,0,1]
	v_pk_fma_f32 v[70:71], v[70:71], s[56:57], v[122:123] op_sel_hi:[1,0,1]
	v_pk_fma_f32 v[78:79], v[78:79], s[56:57], v[126:127] op_sel_hi:[1,0,1]
	v_pk_fma_f32 v[72:73], v[72:73], s[56:57], v[116:117] op_sel_hi:[1,0,1]
	v_pk_fma_f32 v[74:75], v[74:75], s[56:57], v[118:119] op_sel_hi:[1,0,1]
	v_pk_fma_f32 v[52:53], v[52:53], s[56:57], v[120:121] op_sel_hi:[1,0,1]
	v_pk_fma_f32 v[60:61], v[60:61], s[56:57], v[124:125] op_sel_hi:[1,0,1]
	v_pk_fma_f32 v[54:55], v[54:55], s[56:57], v[122:123] op_sel_hi:[1,0,1]
	v_pk_fma_f32 v[62:63], v[62:63], s[56:57], v[126:127] op_sel_hi:[1,0,1]
	v_pk_fma_f32 v[56:57], v[56:57], s[56:57], v[116:117] op_sel_hi:[1,0,1]
	v_pk_fma_f32 v[58:59], v[58:59], s[56:57], v[118:119] op_sel_hi:[1,0,1]
	v_pk_fma_f32 v[36:37], v[36:37], s[56:57], v[120:121] op_sel_hi:[1,0,1]
	v_pk_fma_f32 v[44:45], v[44:45], s[56:57], v[124:125] op_sel_hi:[1,0,1]
	v_pk_fma_f32 v[38:39], v[38:39], s[56:57], v[122:123] op_sel_hi:[1,0,1]
	v_pk_fma_f32 v[46:47], v[46:47], s[56:57], v[126:127] op_sel_hi:[1,0,1]
	v_pk_fma_f32 v[40:41], v[40:41], s[56:57], v[116:117] op_sel_hi:[1,0,1]
	v_pk_fma_f32 v[42:43], v[42:43], s[56:57], v[118:119] op_sel_hi:[1,0,1]
	v_pk_fma_f32 v[20:21], v[20:21], s[56:57], v[120:121] op_sel_hi:[1,0,1]
	v_pk_fma_f32 v[28:29], v[28:29], s[56:57], v[124:125] op_sel_hi:[1,0,1]
	v_pk_fma_f32 v[22:23], v[22:23], s[56:57], v[122:123] op_sel_hi:[1,0,1]
	v_pk_fma_f32 v[30:31], v[30:31], s[56:57], v[126:127] op_sel_hi:[1,0,1]
	v_pk_fma_f32 v[24:25], v[24:25], s[56:57], v[116:117] op_sel_hi:[1,0,1]
	v_pk_fma_f32 v[26:27], v[26:27], s[56:57], v[118:119] op_sel_hi:[1,0,1]
	v_pk_fma_f32 v[4:5], v[4:5], s[56:57], v[120:121] op_sel_hi:[1,0,1]
	v_pk_fma_f32 v[12:13], v[12:13], s[56:57], v[124:125] op_sel_hi:[1,0,1]
	v_pk_fma_f32 v[6:7], v[6:7], s[56:57], v[122:123] op_sel_hi:[1,0,1]
	s_waitcnt vmcnt(6)
;     __device__ __forceinline__ void operator()(const pg8::f32x4 (&acc)[2][2][4][2], const pg8::Unit& u, int wr, int wc, int fr_, int fq_) const {
;     ...
;                 for (int m = 0; m < 4; ++m) {
;                     const int row = row0 + ai * HALF + m * 16;
;                     const u32x4 ca = rc[m][0], cb = rc[m][1];
;                     const f32x4 t1a = acc[ai][0][m][0] * ascale + bv[0][0], t1b = acc[ai][0][m][1] * ascale + bv[0][1];
;                     const f32x4 t2a = acc[ai][1][m][0] * ascale + bv[1][0], t2b = acc[ai][1][m][1] * ascale + bv[1][1];
;                     typedef float f2r __attribute__((ext_vector_type(2)));
;                     u32x4 w1, w2;
;     ...
;                     ROT2(t1a, t2a, ca, 0, w1.x, w2.x) ROT2(t1a, t2a, ca, 1, w1.y, w2.y) ROT2(t1b, t2b, cb, 0, w1.z, w2.z) ROT2(t1b, t2b, cb, 1, w1.w, w2.w)
;     ...
;                     bf16_t* rowp = dst + (size_t)row * pitch + head * HD + dlo;
;                     __builtin_nontemporal_store(w1, (u32x4*)(rowp)); __builtin_nontemporal_store(w2, (u32x4*)(rowp + 64));
	v_lshlrev_b32_e32 v128, 16, v190
	v_lshlrev_b32_e32 v129, 16, v191
	v_and_b32_e32 v190, 0xffff0000, v190
	v_and_b32_e32 v191, 0xffff0000, v191
	v_pk_mul_f32 v[196:197], v[132:133], v[190:191]
	v_pk_fma_f32 v[14:15], v[14:15], s[56:57], v[126:127] op_sel_hi:[1,0,1]
	v_pk_fma_f32 v[196:197], v[140:141], v[128:129], v[196:197] neg_lo:[0,0,1] neg_hi:[0,0,1]
	v_pk_mul_f32 v[128:129], v[132:133], v[128:129]
	v_cvt_pk_bf16_f32 v132, v196, v197
	v_pk_fma_f32 v[8:9], v[8:9], s[56:57], v[116:117] op_sel_hi:[1,0,1]
	v_pk_fma_f32 v[128:129], v[140:141], v[190:191], v[128:129]
	v_lshlrev_b32_e32 v140, 16, v192
	v_lshlrev_b32_e32 v141, 16, v193
	v_and_b32_e32 v190, 0xffff0000, v192
	v_and_b32_e32 v191, 0xffff0000, v193
	v_pk_mul_f32 v[192:193], v[134:135], v[190:191]
	v_pk_mul_f32 v[134:135], v[134:135], v[140:141]
	v_cvt_pk_bf16_f32 v128, v128, v129
	v_pk_fma_f32 v[192:193], v[142:143], v[140:141], v[192:193] neg_lo:[0,0,1] neg_hi:[0,0,1]
	v_pk_fma_f32 v[134:135], v[142:143], v[190:191], v[134:135]
	v_cvt_pk_bf16_f32 v133, v192, v193
	v_and_b32_e32 v140, 0xffff0000, v168
	v_cvt_pk_bf16_f32 v129, v134, v135
	v_lshlrev_b32_e32 v134, 16, v168
	v_lshlrev_b32_e32 v135, 16, v169
	v_and_b32_e32 v141, 0xffff0000, v169
	v_pk_mul_f32 v[142:143], v[130:131], v[140:141]
	v_pk_mul_f32 v[130:131], v[130:131], v[134:135]
	v_pk_fma_f32 v[142:143], v[136:137], v[134:135], v[142:143] neg_lo:[0,0,1] neg_hi:[0,0,1]
	v_pk_fma_f32 v[130:131], v[136:137], v[140:141], v[130:131]
	v_and_b32_e32 v140, 0xffff0000, v170
	v_and_b32_e32 v141, 0xffff0000, v171
	v_cvt_pk_bf16_f32 v134, v142, v143
	v_lshlrev_b32_e32 v136, 16, v170
	v_lshlrev_b32_e32 v137, 16, v171
	v_pk_mul_f32 v[142:143], v[194:195], v[140:141]
	v_cvt_pk_bf16_f32 v130, v130, v131
	v_pk_fma_f32 v[10:11], v[10:11], s[56:57], v[118:119] op_sel_hi:[1,0,1]
	v_pk_fma_f32 v[142:143], v[138:139], v[136:137], v[142:143] neg_lo:[0,0,1] neg_hi:[0,0,1]
	v_pk_mul_f32 v[136:137], v[194:195], v[136:137]
	v_cvt_pk_bf16_f32 v135, v142, v143
	s_nop 0
	v_pk_fma_f32 v[136:137], v[138:139], v[140:141], v[136:137]
	s_nop 0
	v_cvt_pk_bf16_f32 v131, v136, v137
	v_lshlrev_b64 v[136:137], s8, v[174:175]
	v_lshl_add_u64 v[136:137], v[136:137], 1, v[176:177]
	global_store_dwordx4 v[136:137], v[132:135], off
	global_store_dwordx4 v[136:137], v[128:131], off offset:128
	s_waitcnt vmcnt(6)
	v_and_b32_e32 v132, 0xffff0000, v164
	v_and_b32_e32 v133, 0xffff0000, v165
	v_pk_fma_f32 v[130:131], v[98:99], s[56:57], v[114:115] op_sel_hi:[1,0,1]
	v_pk_fma_f32 v[98:99], v[96:97], s[56:57], v[112:113] op_sel_hi:[1,0,1]
	v_lshlrev_b32_e32 v96, 16, v164
	v_lshlrev_b32_e32 v97, 16, v165
	v_pk_mul_f32 v[134:135], v[100:101], v[132:133]
	v_add_u32_e32 v128, 16, v174
	v_pk_fma_f32 v[134:135], v[108:109], v[96:97], v[134:135] neg_lo:[0,0,1] neg_hi:[0,0,1]
	v_pk_mul_f32 v[96:97], v[100:101], v[96:97]
	v_ashrrev_i32_e32 v129, 31, v128
	v_pk_fma_f32 v[100:101], v[108:109], v[132:133], v[96:97]
	v_lshlrev_b32_e32 v108, 16, v166
	v_lshlrev_b32_e32 v109, 16, v167
	v_and_b32_e32 v132, 0xffff0000, v166
	v_and_b32_e32 v133, 0xffff0000, v167
	v_cvt_pk_bf16_f32 v96, v134, v135
	v_pk_mul_f32 v[134:135], v[102:103], v[132:133]
	v_pk_mul_f32 v[102:103], v[102:103], v[108:109]
	v_cvt_pk_bf16_f32 v100, v100, v101
	v_pk_fma_f32 v[134:135], v[110:111], v[108:109], v[134:135] neg_lo:[0,0,1] neg_hi:[0,0,1]
	v_pk_fma_f32 v[102:103], v[110:111], v[132:133], v[102:103]
	v_cvt_pk_bf16_f32 v97, v134, v135
	v_and_b32_e32 v108, 0xffff0000, v160
	v_cvt_pk_bf16_f32 v101, v102, v103
	v_lshlrev_b32_e32 v102, 16, v160
	v_lshlrev_b32_e32 v103, 16, v161
	v_and_b32_e32 v109, 0xffff0000, v161
	v_pk_mul_f32 v[110:111], v[98:99], v[108:109]
	v_pk_mul_f32 v[98:99], v[98:99], v[102:103]
	v_pk_fma_f32 v[110:111], v[104:105], v[102:103], v[110:111] neg_lo:[0,0,1] neg_hi:[0,0,1]
	v_pk_fma_f32 v[102:103], v[104:105], v[108:109], v[98:99]
	v_and_b32_e32 v108, 0xffff0000, v162
	v_and_b32_e32 v109, 0xffff0000, v163
	v_cvt_pk_bf16_f32 v98, v110, v111
	v_lshlrev_b32_e32 v104, 16, v162
	v_lshlrev_b32_e32 v105, 16, v163
	v_pk_mul_f32 v[110:111], v[130:131], v[108:109]
	v_cvt_pk_bf16_f32 v102, v102, v103
	s_nop 0
	v_pk_fma_f32 v[110:111], v[106:107], v[104:105], v[110:111] neg_lo:[0,0,1] neg_hi:[0,0,1]
	v_pk_mul_f32 v[104:105], v[130:131], v[104:105]
	v_cvt_pk_bf16_f32 v99, v110, v111
	s_nop 0
	v_pk_fma_f32 v[104:105], v[106:107], v[108:109], v[104:105]
	s_nop 0
	v_cvt_pk_bf16_f32 v103, v104, v105
	v_lshlrev_b64 v[104:105], s8, v[128:129]
	v_lshl_add_u64 v[104:105], v[104:105], 1, v[176:177]
	global_store_dwordx4 v[104:105], v[96:99], off
	global_store_dwordx4 v[104:105], v[100:103], off offset:128
	s_nop 0
	v_pk_fma_f32 v[98:99], v[82:83], s[56:57], v[114:115] op_sel_hi:[1,0,1]
	s_waitcnt vmcnt(6)
;     __device__ __forceinline__ void operator()(const pg8::f32x4 (&acc)[2][2][4][2], const pg8::Unit& u, int wr, int wc, int fr_, int fq_) const {
;     ...
;                 for (int m = 0; m < 4; ++m) {
;                     const int row = row0 + ai * HALF + m * 16;
;                     const u32x4 ca = rc[m][0], cb = rc[m][1];
;                     const f32x4 t1a = acc[ai][0][m][0] * ascale + bv[0][0], t1b = acc[ai][0][m][1] * ascale + bv[0][1];
;                     const f32x4 t2a = acc[ai][1][m][0] * ascale + bv[1][0], t2b = acc[ai][1][m][1] * ascale + bv[1][1];
;                     typedef float f2r __attribute__((ext_vector_type(2)));
;                     u32x4 w1, w2;
;     ...
;                     ROT2(t1a, t2a, ca, 0, w1.x, w2.x) ROT2(t1a, t2a, ca, 1, w1.y, w2.y) ROT2(t1b, t2b, cb, 0, w1.z, w2.z) ROT2(t1b, t2b, cb, 1, w1.w, w2.w)
;     ...
;                     bf16_t* rowp = dst + (size_t)row * pitch + head * HD + dlo;
;                     __builtin_nontemporal_store(w1, (u32x4*)(rowp)); __builtin_nontemporal_store(w2, (u32x4*)(rowp + 64));
	v_and_b32_e32 v100, 0xffff0000, v156
	v_and_b32_e32 v101, 0xffff0000, v157
	v_pk_fma_f32 v[82:83], v[80:81], s[56:57], v[112:113] op_sel_hi:[1,0,1]
	v_lshlrev_b32_e32 v80, 16, v156
	v_lshlrev_b32_e32 v81, 16, v157
	v_pk_mul_f32 v[102:103], v[84:85], v[100:101]
	v_add_u32_e32 v96, 32, v174
	v_pk_fma_f32 v[102:103], v[92:93], v[80:81], v[102:103] neg_lo:[0,0,1] neg_hi:[0,0,1]
	v_pk_mul_f32 v[80:81], v[84:85], v[80:81]
	v_ashrrev_i32_e32 v97, 31, v96
	v_pk_fma_f32 v[84:85], v[92:93], v[100:101], v[80:81]
	v_lshlrev_b32_e32 v92, 16, v158
	v_lshlrev_b32_e32 v93, 16, v159
	v_and_b32_e32 v100, 0xffff0000, v158
	v_and_b32_e32 v101, 0xffff0000, v159
	v_cvt_pk_bf16_f32 v80, v102, v103
	v_pk_mul_f32 v[102:103], v[86:87], v[100:101]
	v_pk_mul_f32 v[86:87], v[86:87], v[92:93]
	v_cvt_pk_bf16_f32 v84, v84, v85
	v_pk_fma_f32 v[102:103], v[94:95], v[92:93], v[102:103] neg_lo:[0,0,1] neg_hi:[0,0,1]
	v_pk_fma_f32 v[86:87], v[94:95], v[100:101], v[86:87]
	v_cvt_pk_bf16_f32 v81, v102, v103
	v_and_b32_e32 v92, 0xffff0000, v152
	v_cvt_pk_bf16_f32 v85, v86, v87
	v_lshlrev_b32_e32 v86, 16, v152
	v_lshlrev_b32_e32 v87, 16, v153
	v_and_b32_e32 v93, 0xffff0000, v153
	v_pk_mul_f32 v[94:95], v[82:83], v[92:93]
	v_pk_mul_f32 v[82:83], v[82:83], v[86:87]
	v_pk_fma_f32 v[94:95], v[88:89], v[86:87], v[94:95] neg_lo:[0,0,1] neg_hi:[0,0,1]
	v_pk_fma_f32 v[86:87], v[88:89], v[92:93], v[82:83]
	v_and_b32_e32 v92, 0xffff0000, v154
	v_and_b32_e32 v93, 0xffff0000, v155
	v_cvt_pk_bf16_f32 v82, v94, v95
	v_lshlrev_b32_e32 v88, 16, v154
	v_lshlrev_b32_e32 v89, 16, v155
	v_pk_mul_f32 v[94:95], v[98:99], v[92:93]
	v_cvt_pk_bf16_f32 v86, v86, v87
	s_nop 0
	v_pk_fma_f32 v[94:95], v[90:91], v[88:89], v[94:95] neg_lo:[0,0,1] neg_hi:[0,0,1]
	v_pk_mul_f32 v[88:89], v[98:99], v[88:89]
	v_cvt_pk_bf16_f32 v83, v94, v95
	v_pk_fma_f32 v[98:99], v[50:51], s[56:57], v[114:115] op_sel_hi:[1,0,1]
	v_pk_fma_f32 v[88:89], v[90:91], v[92:93], v[88:89]
	v_pk_fma_f32 v[50:51], v[48:49], s[56:57], v[112:113] op_sel_hi:[1,0,1]
	v_cvt_pk_bf16_f32 v87, v88, v89
	v_lshlrev_b64 v[88:89], s8, v[96:97]
	v_lshl_add_u64 v[88:89], v[88:89], 1, v[176:177]
	global_store_dwordx4 v[88:89], v[80:83], off
	global_store_dwordx4 v[88:89], v[84:87], off offset:128
	v_add_u32_e32 v96, 0x80, v174
	v_pk_fma_f32 v[82:83], v[66:67], s[56:57], v[114:115] op_sel_hi:[1,0,1]
	s_waitcnt vmcnt(6)
	v_and_b32_e32 v84, 0xffff0000, v148
	v_and_b32_e32 v85, 0xffff0000, v149
	v_pk_fma_f32 v[66:67], v[64:65], s[56:57], v[112:113] op_sel_hi:[1,0,1]
	v_lshlrev_b32_e32 v64, 16, v148
	v_lshlrev_b32_e32 v65, 16, v149
	v_pk_mul_f32 v[86:87], v[68:69], v[84:85]
	v_add_u32_e32 v80, 48, v174
	v_pk_fma_f32 v[86:87], v[76:77], v[64:65], v[86:87] neg_lo:[0,0,1] neg_hi:[0,0,1]
	v_pk_mul_f32 v[64:65], v[68:69], v[64:65]
	v_ashrrev_i32_e32 v81, 31, v80
	v_pk_fma_f32 v[68:69], v[76:77], v[84:85], v[64:65]
	v_lshlrev_b32_e32 v76, 16, v150
	v_lshlrev_b32_e32 v77, 16, v151
	v_and_b32_e32 v84, 0xffff0000, v150
	v_and_b32_e32 v85, 0xffff0000, v151
	v_cvt_pk_bf16_f32 v64, v86, v87
	v_pk_mul_f32 v[86:87], v[70:71], v[84:85]
	v_pk_mul_f32 v[70:71], v[70:71], v[76:77]
	v_cvt_pk_bf16_f32 v68, v68, v69
	v_pk_fma_f32 v[86:87], v[78:79], v[76:77], v[86:87] neg_lo:[0,0,1] neg_hi:[0,0,1]
	v_pk_fma_f32 v[70:71], v[78:79], v[84:85], v[70:71]
	v_cvt_pk_bf16_f32 v65, v86, v87
	v_and_b32_e32 v76, 0xffff0000, v144
	v_cvt_pk_bf16_f32 v69, v70, v71
	v_lshlrev_b32_e32 v70, 16, v144
	v_lshlrev_b32_e32 v71, 16, v145
	v_and_b32_e32 v77, 0xffff0000, v145
	v_pk_mul_f32 v[78:79], v[66:67], v[76:77]
	v_pk_mul_f32 v[66:67], v[66:67], v[70:71]
	v_pk_fma_f32 v[78:79], v[72:73], v[70:71], v[78:79] neg_lo:[0,0,1] neg_hi:[0,0,1]
	v_pk_fma_f32 v[70:71], v[72:73], v[76:77], v[66:67]
	v_and_b32_e32 v76, 0xffff0000, v146
	v_and_b32_e32 v77, 0xffff0000, v147
	v_cvt_pk_bf16_f32 v66, v78, v79
	v_lshlrev_b32_e32 v72, 16, v146
	v_lshlrev_b32_e32 v73, 16, v147
	v_pk_mul_f32 v[78:79], v[82:83], v[76:77]
	v_cvt_pk_bf16_f32 v70, v70, v71
	v_ashrrev_i32_e32 v97, 31, v96
	v_pk_fma_f32 v[78:79], v[74:75], v[72:73], v[78:79] neg_lo:[0,0,1] neg_hi:[0,0,1]
	v_pk_mul_f32 v[72:73], v[82:83], v[72:73]
	v_cvt_pk_bf16_f32 v67, v78, v79
	s_nop 0
	v_pk_fma_f32 v[72:73], v[74:75], v[76:77], v[72:73]
	s_nop 0
	v_cvt_pk_bf16_f32 v71, v72, v73
	v_lshlrev_b64 v[72:73], s8, v[80:81]
	v_lshl_add_u64 v[72:73], v[72:73], 1, v[176:177]
	global_store_dwordx4 v[72:73], v[64:67], off
	global_store_dwordx4 v[72:73], v[68:71], off offset:128
	s_nop 0
	v_add_u32_e32 v64, 0x2000, v188
	v_and_b32_e32 v172, 0xfffc0, v64
	v_lshl_add_u64 v[64:65], v[172:173], 0, v[178:179]
	v_lshl_add_u64 v[64:65], v[64:65], 2, s[46:47]
	global_load_dwordx4 v[80:83], v[64:65], off offset:16
	global_load_dwordx4 v[84:87], v[64:65], off
	v_add_u32_e32 v64, 0x2400, v188
	v_and_b32_e32 v172, 0xfffc0, v64
	v_lshl_add_u64 v[64:65], v[172:173], 0, v[178:179]
	v_lshl_add_u64 v[64:65], v[64:65], 2, s[46:47]
	global_load_dwordx4 v[88:91], v[64:65], off offset:16
	global_load_dwordx4 v[92:95], v[64:65], off
	v_add_u32_e32 v64, 0x2800, v188
	v_and_b32_e32 v172, 0xfffc0, v64
	v_lshl_add_u64 v[64:65], v[172:173], 0, v[178:179]
	v_lshl_add_u64 v[64:65], v[64:65], 2, s[46:47]
	global_load_dwordx4 v[72:75], v[64:65], off offset:16
	global_load_dwordx4 v[76:79], v[64:65], off
	v_add_u32_e32 v64, 0x2c00, v188
	v_and_b32_e32 v172, 0xfffc0, v64
	v_lshl_add_u64 v[64:65], v[172:173], 0, v[178:179]
	v_lshl_add_u64 v[68:69], v[64:65], 2, s[46:47]
	global_load_dwordx4 v[64:67], v[68:69], off offset:16
	s_nop 0
	global_load_dwordx4 v[68:71], v[68:69], off
	v_mov_b64_e32 v[178:179], v[198:199]
	s_waitcnt vmcnt(6)
;     __device__ __forceinline__ void operator()(const pg8::f32x4 (&acc)[2][2][4][2], const pg8::Unit& u, int wr, int wc, int fr_, int fq_) const {
;     ...
;                 for (int m = 0; m < 4; ++m) {
;                     const int row = row0 + ai * HALF + m * 16;
;                     const u32x4 ca = rc[m][0], cb = rc[m][1];
;                     const f32x4 t1a = acc[ai][0][m][0] * ascale + bv[0][0], t1b = acc[ai][0][m][1] * ascale + bv[0][1];
;                     const f32x4 t2a = acc[ai][1][m][0] * ascale + bv[1][0], t2b = acc[ai][1][m][1] * ascale + bv[1][1];
;                     typedef float f2r __attribute__((ext_vector_type(2)));
;                     u32x4 w1, w2;
;     ...
;                     ROT2(t1a, t2a, ca, 0, w1.x, w2.x) ROT2(t1a, t2a, ca, 1, w1.y, w2.y) ROT2(t1b, t2b, cb, 0, w1.z, w2.z) ROT2(t1b, t2b, cb, 1, w1.w, w2.w)
;     ...
;                     bf16_t* rowp = dst + (size_t)row * pitch + head * HD + dlo;
;                     __builtin_nontemporal_store(w1, (u32x4*)(rowp)); __builtin_nontemporal_store(w2, (u32x4*)(rowp + 64));
	v_lshlrev_b32_e32 v48, 16, v84
	v_lshlrev_b32_e32 v49, 16, v85
	v_and_b32_e32 v84, 0xffff0000, v84
	v_and_b32_e32 v85, 0xffff0000, v85
	v_pk_mul_f32 v[100:101], v[52:53], v[84:85]
	s_nop 0
	v_pk_fma_f32 v[100:101], v[60:61], v[48:49], v[100:101] neg_lo:[0,0,1] neg_hi:[0,0,1]
	v_pk_mul_f32 v[48:49], v[52:53], v[48:49]
	s_nop 0
	v_pk_fma_f32 v[52:53], v[60:61], v[84:85], v[48:49]
	v_lshlrev_b32_e32 v60, 16, v86
	v_lshlrev_b32_e32 v61, 16, v87
	v_and_b32_e32 v84, 0xffff0000, v86
	v_and_b32_e32 v85, 0xffff0000, v87
	v_pk_mul_f32 v[86:87], v[54:55], v[84:85]
	v_pk_mul_f32 v[54:55], v[54:55], v[60:61]
	v_cvt_pk_bf16_f32 v48, v100, v101
	v_cvt_pk_bf16_f32 v52, v52, v53
	v_pk_fma_f32 v[86:87], v[62:63], v[60:61], v[86:87] neg_lo:[0,0,1] neg_hi:[0,0,1]
	v_pk_fma_f32 v[54:55], v[62:63], v[84:85], v[54:55]
	v_cvt_pk_bf16_f32 v49, v86, v87
	v_and_b32_e32 v60, 0xffff0000, v80
	v_cvt_pk_bf16_f32 v53, v54, v55
	v_lshlrev_b32_e32 v54, 16, v80
	v_lshlrev_b32_e32 v55, 16, v81
	v_and_b32_e32 v61, 0xffff0000, v81
	v_pk_mul_f32 v[62:63], v[50:51], v[60:61]
	v_pk_mul_f32 v[50:51], v[50:51], v[54:55]
	v_pk_fma_f32 v[62:63], v[56:57], v[54:55], v[62:63] neg_lo:[0,0,1] neg_hi:[0,0,1]
	v_pk_fma_f32 v[54:55], v[56:57], v[60:61], v[50:51]
	v_and_b32_e32 v60, 0xffff0000, v82
	v_and_b32_e32 v61, 0xffff0000, v83
	v_cvt_pk_bf16_f32 v50, v62, v63
	v_lshlrev_b32_e32 v56, 16, v82
	v_lshlrev_b32_e32 v57, 16, v83
	v_pk_mul_f32 v[62:63], v[98:99], v[60:61]
	v_cvt_pk_bf16_f32 v54, v54, v55
	s_nop 0
	v_pk_fma_f32 v[62:63], v[58:59], v[56:57], v[62:63] neg_lo:[0,0,1] neg_hi:[0,0,1]
	v_pk_mul_f32 v[56:57], v[98:99], v[56:57]
	v_cvt_pk_bf16_f32 v51, v62, v63
	s_nop 0
	v_pk_fma_f32 v[56:57], v[58:59], v[60:61], v[56:57]
	s_nop 0
	v_cvt_pk_bf16_f32 v55, v56, v57
	v_lshlrev_b64 v[56:57], s8, v[96:97]
	v_lshl_add_u64 v[56:57], v[56:57], 1, v[176:177]
	global_store_dwordx4 v[56:57], v[48:51], off
	global_store_dwordx4 v[56:57], v[52:55], off offset:128
	s_nop 0
	v_pk_fma_f32 v[50:51], v[34:35], s[56:57], v[114:115] op_sel_hi:[1,0,1]
	s_waitcnt vmcnt(6)
	v_and_b32_e32 v52, 0xffff0000, v92
	v_and_b32_e32 v53, 0xffff0000, v93
	v_pk_fma_f32 v[34:35], v[32:33], s[56:57], v[112:113] op_sel_hi:[1,0,1]
	v_lshlrev_b32_e32 v32, 16, v92
	v_lshlrev_b32_e32 v33, 16, v93
	v_pk_mul_f32 v[54:55], v[36:37], v[52:53]
	v_add_u32_e32 v48, 0x90, v174
	v_pk_fma_f32 v[54:55], v[44:45], v[32:33], v[54:55] neg_lo:[0,0,1] neg_hi:[0,0,1]
	v_pk_mul_f32 v[32:33], v[36:37], v[32:33]
	v_ashrrev_i32_e32 v49, 31, v48
	v_pk_fma_f32 v[36:37], v[44:45], v[52:53], v[32:33]
	v_lshlrev_b32_e32 v44, 16, v94
	v_lshlrev_b32_e32 v45, 16, v95
	v_and_b32_e32 v52, 0xffff0000, v94
	v_and_b32_e32 v53, 0xffff0000, v95
	v_cvt_pk_bf16_f32 v32, v54, v55
	v_pk_mul_f32 v[54:55], v[38:39], v[52:53]
	v_pk_mul_f32 v[38:39], v[38:39], v[44:45]
	v_cvt_pk_bf16_f32 v36, v36, v37
	v_pk_fma_f32 v[54:55], v[46:47], v[44:45], v[54:55] neg_lo:[0,0,1] neg_hi:[0,0,1]
	v_pk_fma_f32 v[38:39], v[46:47], v[52:53], v[38:39]
	v_cvt_pk_bf16_f32 v33, v54, v55
	v_and_b32_e32 v44, 0xffff0000, v88
	v_cvt_pk_bf16_f32 v37, v38, v39
	v_lshlrev_b32_e32 v38, 16, v88
	v_lshlrev_b32_e32 v39, 16, v89
	v_and_b32_e32 v45, 0xffff0000, v89
	v_pk_mul_f32 v[46:47], v[34:35], v[44:45]
	v_pk_mul_f32 v[34:35], v[34:35], v[38:39]
	v_pk_fma_f32 v[46:47], v[40:41], v[38:39], v[46:47] neg_lo:[0,0,1] neg_hi:[0,0,1]
	v_pk_fma_f32 v[38:39], v[40:41], v[44:45], v[34:35]
	v_and_b32_e32 v44, 0xffff0000, v90
	v_and_b32_e32 v45, 0xffff0000, v91
	v_cvt_pk_bf16_f32 v34, v46, v47
	v_lshlrev_b32_e32 v40, 16, v90
	v_lshlrev_b32_e32 v41, 16, v91
	v_pk_mul_f32 v[46:47], v[50:51], v[44:45]
	v_cvt_pk_bf16_f32 v38, v38, v39
	s_nop 0
	v_pk_fma_f32 v[46:47], v[42:43], v[40:41], v[46:47] neg_lo:[0,0,1] neg_hi:[0,0,1]
	v_pk_mul_f32 v[40:41], v[50:51], v[40:41]
	v_cvt_pk_bf16_f32 v35, v46, v47
	s_nop 0
	v_pk_fma_f32 v[40:41], v[42:43], v[44:45], v[40:41]
	s_nop 0
	v_cvt_pk_bf16_f32 v39, v40, v41
	v_lshlrev_b64 v[40:41], s8, v[48:49]
	v_lshl_add_u64 v[40:41], v[40:41], 1, v[176:177]
	global_store_dwordx4 v[40:41], v[32:35], off
	global_store_dwordx4 v[40:41], v[36:39], off offset:128
	s_nop 0
	v_pk_fma_f32 v[34:35], v[18:19], s[56:57], v[114:115] op_sel_hi:[1,0,1]
	s_waitcnt vmcnt(6)
;     __device__ __forceinline__ void operator()(const pg8::f32x4 (&acc)[2][2][4][2], const pg8::Unit& u, int wr, int wc, int fr_, int fq_) const {
;     ...
;                 for (int m = 0; m < 4; ++m) {
;                     const int row = row0 + ai * HALF + m * 16;
;                     const u32x4 ca = rc[m][0], cb = rc[m][1];
;                     const f32x4 t1a = acc[ai][0][m][0] * ascale + bv[0][0], t1b = acc[ai][0][m][1] * ascale + bv[0][1];
;                     const f32x4 t2a = acc[ai][1][m][0] * ascale + bv[1][0], t2b = acc[ai][1][m][1] * ascale + bv[1][1];
;                     typedef float f2r __attribute__((ext_vector_type(2)));
;                     u32x4 w1, w2;
;     ...
;                     ROT2(t1a, t2a, ca, 0, w1.x, w2.x) ROT2(t1a, t2a, ca, 1, w1.y, w2.y) ROT2(t1b, t2b, cb, 0, w1.z, w2.z) ROT2(t1b, t2b, cb, 1, w1.w, w2.w)
;     ...
;                     bf16_t* rowp = dst + (size_t)row * pitch + head * HD + dlo;
;                     __builtin_nontemporal_store(w1, (u32x4*)(rowp)); __builtin_nontemporal_store(w2, (u32x4*)(rowp + 64));
	v_and_b32_e32 v36, 0xffff0000, v76
	v_and_b32_e32 v37, 0xffff0000, v77
	v_pk_fma_f32 v[18:19], v[16:17], s[56:57], v[112:113] op_sel_hi:[1,0,1]
	v_lshlrev_b32_e32 v16, 16, v76
	v_lshlrev_b32_e32 v17, 16, v77
	v_pk_mul_f32 v[38:39], v[20:21], v[36:37]
	v_add_u32_e32 v32, 0xa0, v174
	v_pk_fma_f32 v[38:39], v[28:29], v[16:17], v[38:39] neg_lo:[0,0,1] neg_hi:[0,0,1]
	v_pk_mul_f32 v[16:17], v[20:21], v[16:17]
	v_ashrrev_i32_e32 v33, 31, v32
	v_pk_fma_f32 v[20:21], v[28:29], v[36:37], v[16:17]
	v_lshlrev_b32_e32 v28, 16, v78
	v_lshlrev_b32_e32 v29, 16, v79
	v_and_b32_e32 v36, 0xffff0000, v78
	v_and_b32_e32 v37, 0xffff0000, v79
	v_cvt_pk_bf16_f32 v16, v38, v39
	v_pk_mul_f32 v[38:39], v[22:23], v[36:37]
	v_pk_mul_f32 v[22:23], v[22:23], v[28:29]
	v_cvt_pk_bf16_f32 v20, v20, v21
	v_pk_fma_f32 v[38:39], v[30:31], v[28:29], v[38:39] neg_lo:[0,0,1] neg_hi:[0,0,1]
	v_pk_fma_f32 v[22:23], v[30:31], v[36:37], v[22:23]
	v_cvt_pk_bf16_f32 v17, v38, v39
	v_and_b32_e32 v28, 0xffff0000, v72
	v_cvt_pk_bf16_f32 v21, v22, v23
	v_lshlrev_b32_e32 v22, 16, v72
	v_lshlrev_b32_e32 v23, 16, v73
	v_and_b32_e32 v29, 0xffff0000, v73
	v_pk_mul_f32 v[30:31], v[18:19], v[28:29]
	v_pk_mul_f32 v[18:19], v[18:19], v[22:23]
	v_pk_fma_f32 v[30:31], v[24:25], v[22:23], v[30:31] neg_lo:[0,0,1] neg_hi:[0,0,1]
	v_pk_fma_f32 v[22:23], v[24:25], v[28:29], v[18:19]
	v_and_b32_e32 v28, 0xffff0000, v74
	v_and_b32_e32 v29, 0xffff0000, v75
	v_cvt_pk_bf16_f32 v18, v30, v31
	v_lshlrev_b32_e32 v24, 16, v74
	v_lshlrev_b32_e32 v25, 16, v75
	v_pk_mul_f32 v[30:31], v[34:35], v[28:29]
	v_cvt_pk_bf16_f32 v22, v22, v23
	s_nop 0
	v_pk_fma_f32 v[30:31], v[26:27], v[24:25], v[30:31] neg_lo:[0,0,1] neg_hi:[0,0,1]
	v_pk_mul_f32 v[24:25], v[34:35], v[24:25]
	v_cvt_pk_bf16_f32 v19, v30, v31
	s_nop 0
	v_pk_fma_f32 v[24:25], v[26:27], v[28:29], v[24:25]
	s_nop 0
	v_cvt_pk_bf16_f32 v23, v24, v25
	v_lshlrev_b64 v[24:25], s8, v[32:33]
	v_lshl_add_u64 v[24:25], v[24:25], 1, v[176:177]
	global_store_dwordx4 v[24:25], v[16:19], off
	global_store_dwordx4 v[24:25], v[20:23], off offset:128
	s_nop 0
	v_pk_fma_f32 v[18:19], v[2:3], s[56:57], v[114:115] op_sel_hi:[1,0,1]
	s_waitcnt vmcnt(6)
	v_and_b32_e32 v20, 0xffff0000, v68
	v_and_b32_e32 v21, 0xffff0000, v69
	v_pk_fma_f32 v[2:3], v[0:1], s[56:57], v[112:113] op_sel_hi:[1,0,1]
	v_lshlrev_b32_e32 v0, 16, v68
	v_lshlrev_b32_e32 v1, 16, v69
	v_pk_mul_f32 v[22:23], v[4:5], v[20:21]
	v_add_u32_e32 v16, 0xb0, v174
	v_pk_fma_f32 v[22:23], v[12:13], v[0:1], v[22:23] neg_lo:[0,0,1] neg_hi:[0,0,1]
	v_pk_mul_f32 v[0:1], v[4:5], v[0:1]
	v_ashrrev_i32_e32 v17, 31, v16
	v_pk_fma_f32 v[4:5], v[12:13], v[20:21], v[0:1]
	v_lshlrev_b32_e32 v12, 16, v70
	v_lshlrev_b32_e32 v13, 16, v71
	v_and_b32_e32 v20, 0xffff0000, v70
	v_and_b32_e32 v21, 0xffff0000, v71
	v_cvt_pk_bf16_f32 v0, v22, v23
	v_pk_mul_f32 v[22:23], v[6:7], v[20:21]
	v_pk_mul_f32 v[6:7], v[6:7], v[12:13]
	v_cvt_pk_bf16_f32 v4, v4, v5
	v_pk_fma_f32 v[22:23], v[14:15], v[12:13], v[22:23] neg_lo:[0,0,1] neg_hi:[0,0,1]
	v_pk_fma_f32 v[6:7], v[14:15], v[20:21], v[6:7]
	v_cvt_pk_bf16_f32 v1, v22, v23
	v_and_b32_e32 v12, 0xffff0000, v64
	v_cvt_pk_bf16_f32 v5, v6, v7
	v_lshlrev_b32_e32 v6, 16, v64
	v_lshlrev_b32_e32 v7, 16, v65
	v_and_b32_e32 v13, 0xffff0000, v65
	v_pk_mul_f32 v[14:15], v[2:3], v[12:13]
	v_pk_mul_f32 v[2:3], v[2:3], v[6:7]
	v_pk_fma_f32 v[14:15], v[8:9], v[6:7], v[14:15] neg_lo:[0,0,1] neg_hi:[0,0,1]
	v_pk_fma_f32 v[6:7], v[8:9], v[12:13], v[2:3]
	v_and_b32_e32 v12, 0xffff0000, v66
	v_and_b32_e32 v13, 0xffff0000, v67
	v_cvt_pk_bf16_f32 v2, v14, v15
	v_lshlrev_b32_e32 v8, 16, v66
	v_lshlrev_b32_e32 v9, 16, v67
	v_pk_mul_f32 v[14:15], v[18:19], v[12:13]
	v_cvt_pk_bf16_f32 v6, v6, v7
	s_nop 0
	v_pk_fma_f32 v[14:15], v[10:11], v[8:9], v[14:15] neg_lo:[0,0,1] neg_hi:[0,0,1]
	v_pk_mul_f32 v[8:9], v[18:19], v[8:9]
	v_cvt_pk_bf16_f32 v3, v14, v15
	s_nop 0
	v_pk_fma_f32 v[8:9], v[10:11], v[12:13], v[8:9]
	s_nop 0
	v_cvt_pk_bf16_f32 v7, v8, v9
	v_lshlrev_b64 v[8:9], s8, v[16:17]
	v_lshl_add_u64 v[8:9], v[8:9], 1, v[176:177]
	global_store_dwordx4 v[8:9], v[0:3], off
	global_store_dwordx4 v[8:9], v[4:7], off offset:128
	s_andn2_b64 vcc, exec, s[0:1]
	s_mov_b64 s[0:1], -1
	s_cbranch_vccnz .LBB0_407
	s_branch .LBB0_441

; __device__ __forceinline__ unsigned cvt_pk_bf16(float lo, float hi) { unsigned r; asm volatile("v_cvt_pk_bf16_f32 %0, %1, %2" : "=v"(r) : "v"(lo), "v"(hi)); return r; }
;     __device__ __forceinline__ void operator()(const pg8::f32x4 (&acc)[2][2][4][2], const pg8::Unit& u, int wr, int wc, int fr_, int fq_) const {
;     ...
;             else if (vt == 19) { dst = (bf16_t*)(ws + WS_V); pitch = DKV; coff = 0; }
;     ...
; #pragma unroll
;             for (int ai = 0; ai < 2; ++ai)
; #pragma unroll
;                 for (int m = 0; m < 4; ++m) { bf16_t* rowp = dst + (size_t)(row0 + ai * HALF + m * 16) * pitch + col0;
; #pragma unroll
;                     for (int bj = 0; bj < 2; ++bj) { const f32x4 v0 = acc[ai][bj][m][0] * ascale + bv[bj][0], v1 = acc[ai][bj][m][1] * ascale + bv[bj][1];
;                         u32x4 w; w.x = cvt_pk_bf16(v0[0], v0[1]); w.y = cvt_pk_bf16(v0[2], v0[3]); w.z = cvt_pk_bf16(v1[0], v1[1]); w.w = cvt_pk_bf16(v1[2], v1[3]);
;                         __builtin_nontemporal_store(w, (u32x4*)(rowp + bj * HALF)); } }
.LBB0_433:
	v_add_u32_e32 v144, s9, v144
	v_ashrrev_i32_e32 v147, 31, v174
	v_ashrrev_i32_e32 v145, 31, v144
	v_mul_lo_u32 v147, s64, v147
	v_mad_u64_u32 v[148:149], s[6:7], s64, v174, 0
	v_lshl_add_u64 v[144:145], v[144:145], 1, s[68:69]
	v_add3_u32 v149, v149, v147, v163
	v_lshl_add_u64 v[152:153], v[148:149], 1, v[144:145]
	s_waitcnt vmcnt(2)
	v_pk_fma_f32 v[148:149], v[140:141], s[56:57], v[124:125] op_sel_hi:[1,0,1]
	v_pk_fma_f32 v[150:151], v[142:143], s[56:57], v[126:127] op_sel_hi:[1,0,1]
	v_cvt_pk_bf16_f32 v148, v148, v149
	v_pk_fma_f32 v[154:155], v[138:139], s[56:57], v[118:119] op_sel_hi:[1,0,1]
	v_cvt_pk_bf16_f32 v149, v150, v151
	v_pk_fma_f32 v[156:157], v[136:137], s[56:57], v[116:117] op_sel_hi:[1,0,1]
	v_add_u32_e32 v147, 16, v174
	v_cvt_pk_bf16_f32 v150, v156, v157
	v_cvt_pk_bf16_f32 v151, v154, v155
	global_store_dwordx4 v[152:153], v[148:151], off
	s_waitcnt vmcnt(2)
	v_pk_fma_f32 v[154:155], v[130:131], s[56:57], v[114:115] op_sel_hi:[1,0,1]
	v_pk_fma_f32 v[156:157], v[128:129], s[56:57], v[112:113] op_sel_hi:[1,0,1]
	s_waitcnt vmcnt(1)
	v_pk_fma_f32 v[148:149], v[132:133], s[56:57], v[120:121] op_sel_hi:[1,0,1]
	v_pk_fma_f32 v[150:151], v[134:135], s[56:57], v[122:123] op_sel_hi:[1,0,1]
	v_cvt_pk_bf16_f32 v148, v148, v149
	s_mov_b64 s[70:71], 0
	v_cvt_pk_bf16_f32 v149, v150, v151
	v_cvt_pk_bf16_f32 v150, v156, v157
	v_cvt_pk_bf16_f32 v151, v154, v155
	global_store_dwordx4 v[152:153], v[148:151], off offset:256
	v_pk_fma_f32 v[154:155], v[106:107], s[56:57], v[118:119] op_sel_hi:[1,0,1]
	v_pk_fma_f32 v[156:157], v[104:105], s[56:57], v[116:117] op_sel_hi:[1,0,1]
	v_ashrrev_i32_e32 v148, 31, v147
	v_mul_lo_u32 v150, s64, v148
	v_mul_lo_u32 v151, s65, v147
	v_mad_u64_u32 v[148:149], s[6:7], s64, v147, 0
	v_add3_u32 v149, v149, v150, v151
	v_lshl_add_u64 v[152:153], v[148:149], 1, v[144:145]
	v_pk_fma_f32 v[148:149], v[108:109], s[56:57], v[124:125] op_sel_hi:[1,0,1]
	v_pk_fma_f32 v[150:151], v[110:111], s[56:57], v[126:127] op_sel_hi:[1,0,1]
	v_cvt_pk_bf16_f32 v148, v148, v149
	v_add_u32_e32 v147, 32, v174
	v_cvt_pk_bf16_f32 v149, v150, v151
	v_cvt_pk_bf16_f32 v150, v156, v157
	v_cvt_pk_bf16_f32 v151, v154, v155
	global_store_dwordx4 v[152:153], v[148:151], off
	v_pk_fma_f32 v[154:155], v[98:99], s[56:57], v[114:115] op_sel_hi:[1,0,1]
	v_pk_fma_f32 v[156:157], v[96:97], s[56:57], v[112:113] op_sel_hi:[1,0,1]
	v_pk_fma_f32 v[148:149], v[100:101], s[56:57], v[120:121] op_sel_hi:[1,0,1]
	v_pk_fma_f32 v[150:151], v[102:103], s[56:57], v[122:123] op_sel_hi:[1,0,1]
	v_cvt_pk_bf16_f32 v148, v148, v149
	s_nop 0
	v_cvt_pk_bf16_f32 v149, v150, v151
	v_cvt_pk_bf16_f32 v150, v156, v157
	v_cvt_pk_bf16_f32 v151, v154, v155
	global_store_dwordx4 v[152:153], v[148:151], off offset:256
	v_pk_fma_f32 v[154:155], v[90:91], s[56:57], v[118:119] op_sel_hi:[1,0,1]
	v_pk_fma_f32 v[156:157], v[88:89], s[56:57], v[116:117] op_sel_hi:[1,0,1]
	v_ashrrev_i32_e32 v148, 31, v147
	v_mul_lo_u32 v150, s64, v148
	v_mul_lo_u32 v151, s65, v147
	v_mad_u64_u32 v[148:149], s[6:7], s64, v147, 0
	v_add3_u32 v149, v149, v150, v151
	v_lshl_add_u64 v[152:153], v[148:149], 1, v[144:145]
	v_pk_fma_f32 v[148:149], v[92:93], s[56:57], v[124:125] op_sel_hi:[1,0,1]
	v_pk_fma_f32 v[150:151], v[94:95], s[56:57], v[126:127] op_sel_hi:[1,0,1]
	v_cvt_pk_bf16_f32 v148, v148, v149
	v_add_u32_e32 v147, 48, v174
	v_cvt_pk_bf16_f32 v149, v150, v151
	v_cvt_pk_bf16_f32 v150, v156, v157
	v_cvt_pk_bf16_f32 v151, v154, v155
	global_store_dwordx4 v[152:153], v[148:151], off
	v_pk_fma_f32 v[154:155], v[82:83], s[56:57], v[114:115] op_sel_hi:[1,0,1]
	v_pk_fma_f32 v[156:157], v[80:81], s[56:57], v[112:113] op_sel_hi:[1,0,1]
	v_pk_fma_f32 v[148:149], v[84:85], s[56:57], v[120:121] op_sel_hi:[1,0,1]
	v_pk_fma_f32 v[150:151], v[86:87], s[56:57], v[122:123] op_sel_hi:[1,0,1]
	v_cvt_pk_bf16_f32 v148, v148, v149
	s_nop 0
	v_cvt_pk_bf16_f32 v149, v150, v151
	v_cvt_pk_bf16_f32 v150, v156, v157
	v_cvt_pk_bf16_f32 v151, v154, v155
	global_store_dwordx4 v[152:153], v[148:151], off offset:256
	v_pk_fma_f32 v[154:155], v[74:75], s[56:57], v[118:119] op_sel_hi:[1,0,1]
	v_pk_fma_f32 v[156:157], v[72:73], s[56:57], v[116:117] op_sel_hi:[1,0,1]
	v_ashrrev_i32_e32 v148, 31, v147
	v_mul_lo_u32 v150, s64, v148
	v_mul_lo_u32 v151, s65, v147
	v_mad_u64_u32 v[148:149], s[6:7], s64, v147, 0
	v_add3_u32 v149, v149, v150, v151
	v_lshl_add_u64 v[152:153], v[148:149], 1, v[144:145]
	v_pk_fma_f32 v[148:149], v[76:77], s[56:57], v[124:125] op_sel_hi:[1,0,1]
	v_pk_fma_f32 v[150:151], v[78:79], s[56:57], v[126:127] op_sel_hi:[1,0,1]
	v_cvt_pk_bf16_f32 v148, v148, v149
	v_add_u32_e32 v147, 0x80, v174
	v_cvt_pk_bf16_f32 v149, v150, v151
	v_cvt_pk_bf16_f32 v150, v156, v157
	v_cvt_pk_bf16_f32 v151, v154, v155
	global_store_dwordx4 v[152:153], v[148:151], off
	v_pk_fma_f32 v[154:155], v[66:67], s[56:57], v[114:115] op_sel_hi:[1,0,1]
	v_pk_fma_f32 v[156:157], v[64:65], s[56:57], v[112:113] op_sel_hi:[1,0,1]
	v_pk_fma_f32 v[148:149], v[68:69], s[56:57], v[120:121] op_sel_hi:[1,0,1]
	v_pk_fma_f32 v[150:151], v[70:71], s[56:57], v[122:123] op_sel_hi:[1,0,1]
	v_cvt_pk_bf16_f32 v148, v148, v149
	s_nop 0
	v_cvt_pk_bf16_f32 v149, v150, v151
	v_cvt_pk_bf16_f32 v150, v156, v157
; __device__ __forceinline__ unsigned cvt_pk_bf16(float lo, float hi) { unsigned r; asm volatile("v_cvt_pk_bf16_f32 %0, %1, %2" : "=v"(r) : "v"(lo), "v"(hi)); return r; }
;     __device__ __forceinline__ void operator()(const pg8::f32x4 (&acc)[2][2][4][2], const pg8::Unit& u, int wr, int wc, int fr_, int fq_) const {
;     ...
;             else if (vt == 19) { dst = (bf16_t*)(ws + WS_V); pitch = DKV; coff = 0; }
;     ...
; #pragma unroll
;             for (int ai = 0; ai < 2; ++ai)
; #pragma unroll
;                 for (int m = 0; m < 4; ++m) { bf16_t* rowp = dst + (size_t)(row0 + ai * HALF + m * 16) * pitch + col0;
; #pragma unroll
;                     for (int bj = 0; bj < 2; ++bj) { const f32x4 v0 = acc[ai][bj][m][0] * ascale + bv[bj][0], v1 = acc[ai][bj][m][1] * ascale + bv[bj][1];
;                         u32x4 w; w.x = cvt_pk_bf16(v0[0], v0[1]); w.y = cvt_pk_bf16(v0[2], v0[3]); w.z = cvt_pk_bf16(v1[0], v1[1]); w.w = cvt_pk_bf16(v1[2], v1[3]);
;                         __builtin_nontemporal_store(w, (u32x4*)(rowp + bj * HALF)); } }
	v_cvt_pk_bf16_f32 v151, v154, v155
	global_store_dwordx4 v[152:153], v[148:151], off offset:256
	v_pk_fma_f32 v[154:155], v[58:59], s[56:57], v[118:119] op_sel_hi:[1,0,1]
	v_pk_fma_f32 v[156:157], v[56:57], s[56:57], v[116:117] op_sel_hi:[1,0,1]
	v_ashrrev_i32_e32 v148, 31, v147
	v_mul_lo_u32 v150, s64, v148
	v_mul_lo_u32 v151, s65, v147
	v_mad_u64_u32 v[148:149], s[6:7], s64, v147, 0
	v_add3_u32 v149, v149, v150, v151
	v_lshl_add_u64 v[152:153], v[148:149], 1, v[144:145]
	v_pk_fma_f32 v[148:149], v[60:61], s[56:57], v[124:125] op_sel_hi:[1,0,1]
	v_pk_fma_f32 v[150:151], v[62:63], s[56:57], v[126:127] op_sel_hi:[1,0,1]
	v_cvt_pk_bf16_f32 v148, v148, v149
	v_add_u32_e32 v147, 0x90, v174
	v_cvt_pk_bf16_f32 v149, v150, v151
	v_cvt_pk_bf16_f32 v150, v156, v157
	v_cvt_pk_bf16_f32 v151, v154, v155
	global_store_dwordx4 v[152:153], v[148:151], off
	v_pk_fma_f32 v[154:155], v[50:51], s[56:57], v[114:115] op_sel_hi:[1,0,1]
	v_pk_fma_f32 v[156:157], v[48:49], s[56:57], v[112:113] op_sel_hi:[1,0,1]
	v_pk_fma_f32 v[148:149], v[52:53], s[56:57], v[120:121] op_sel_hi:[1,0,1]
	v_pk_fma_f32 v[150:151], v[54:55], s[56:57], v[122:123] op_sel_hi:[1,0,1]
	v_cvt_pk_bf16_f32 v148, v148, v149
	s_nop 0
	v_cvt_pk_bf16_f32 v149, v150, v151
	v_cvt_pk_bf16_f32 v150, v156, v157
	v_cvt_pk_bf16_f32 v151, v154, v155
	global_store_dwordx4 v[152:153], v[148:151], off offset:256
	v_pk_fma_f32 v[154:155], v[42:43], s[56:57], v[118:119] op_sel_hi:[1,0,1]
	v_pk_fma_f32 v[156:157], v[40:41], s[56:57], v[116:117] op_sel_hi:[1,0,1]
	v_ashrrev_i32_e32 v148, 31, v147
	v_mul_lo_u32 v150, s64, v148
	v_mul_lo_u32 v151, s65, v147
	v_mad_u64_u32 v[148:149], s[6:7], s64, v147, 0
	v_add3_u32 v149, v149, v150, v151
	v_lshl_add_u64 v[152:153], v[148:149], 1, v[144:145]
	v_pk_fma_f32 v[148:149], v[44:45], s[56:57], v[124:125] op_sel_hi:[1,0,1]
	v_pk_fma_f32 v[150:151], v[46:47], s[56:57], v[126:127] op_sel_hi:[1,0,1]
	v_cvt_pk_bf16_f32 v148, v148, v149
	v_add_u32_e32 v147, 0xa0, v174
	v_cvt_pk_bf16_f32 v149, v150, v151
	v_cvt_pk_bf16_f32 v150, v156, v157
	v_cvt_pk_bf16_f32 v151, v154, v155
	global_store_dwordx4 v[152:153], v[148:151], off
	v_pk_fma_f32 v[154:155], v[34:35], s[56:57], v[114:115] op_sel_hi:[1,0,1]
	v_pk_fma_f32 v[156:157], v[32:33], s[56:57], v[112:113] op_sel_hi:[1,0,1]
	v_pk_fma_f32 v[148:149], v[36:37], s[56:57], v[120:121] op_sel_hi:[1,0,1]
	v_pk_fma_f32 v[150:151], v[38:39], s[56:57], v[122:123] op_sel_hi:[1,0,1]
	v_cvt_pk_bf16_f32 v148, v148, v149
	s_nop 0
	v_cvt_pk_bf16_f32 v149, v150, v151
	v_cvt_pk_bf16_f32 v150, v156, v157
	v_cvt_pk_bf16_f32 v151, v154, v155
	global_store_dwordx4 v[152:153], v[148:151], off offset:256
	v_pk_fma_f32 v[154:155], v[26:27], s[56:57], v[118:119] op_sel_hi:[1,0,1]
	v_pk_fma_f32 v[156:157], v[24:25], s[56:57], v[116:117] op_sel_hi:[1,0,1]
	v_ashrrev_i32_e32 v148, 31, v147
	v_mul_lo_u32 v150, s64, v148
	v_mul_lo_u32 v151, s65, v147
	v_mad_u64_u32 v[148:149], s[6:7], s64, v147, 0
	v_add3_u32 v149, v149, v150, v151
	v_lshl_add_u64 v[152:153], v[148:149], 1, v[144:145]
	v_pk_fma_f32 v[148:149], v[28:29], s[56:57], v[124:125] op_sel_hi:[1,0,1]
	v_pk_fma_f32 v[150:151], v[30:31], s[56:57], v[126:127] op_sel_hi:[1,0,1]
	v_cvt_pk_bf16_f32 v148, v148, v149
	v_add_u32_e32 v147, 0xb0, v174
	v_cvt_pk_bf16_f32 v149, v150, v151
	v_cvt_pk_bf16_f32 v150, v156, v157
	v_cvt_pk_bf16_f32 v151, v154, v155
	global_store_dwordx4 v[152:153], v[148:151], off
	v_pk_fma_f32 v[154:155], v[18:19], s[56:57], v[114:115] op_sel_hi:[1,0,1]
	v_pk_fma_f32 v[156:157], v[16:17], s[56:57], v[112:113] op_sel_hi:[1,0,1]
	v_pk_fma_f32 v[148:149], v[20:21], s[56:57], v[120:121] op_sel_hi:[1,0,1]
	v_pk_fma_f32 v[150:151], v[22:23], s[56:57], v[122:123] op_sel_hi:[1,0,1]
	v_cvt_pk_bf16_f32 v148, v148, v149
	s_nop 0
	v_cvt_pk_bf16_f32 v149, v150, v151
	v_cvt_pk_bf16_f32 v150, v156, v157
	v_cvt_pk_bf16_f32 v151, v154, v155
	global_store_dwordx4 v[152:153], v[148:151], off offset:256
	v_pk_fma_f32 v[152:153], v[10:11], s[56:57], v[118:119] op_sel_hi:[1,0,1]
	v_pk_fma_f32 v[154:155], v[8:9], s[56:57], v[116:117] op_sel_hi:[1,0,1]
	v_ashrrev_i32_e32 v148, 31, v147
	v_mul_lo_u32 v150, s64, v148
	v_mul_lo_u32 v151, s65, v147
	v_mad_u64_u32 v[148:149], s[6:7], s64, v147, 0
	v_add3_u32 v149, v149, v150, v151
	v_lshl_add_u64 v[144:145], v[148:149], 1, v[144:145]
	v_pk_fma_f32 v[150:151], v[14:15], s[56:57], v[126:127] op_sel_hi:[1,0,1]
	v_pk_fma_f32 v[148:149], v[12:13], s[56:57], v[124:125] op_sel_hi:[1,0,1]
	s_nop 0
	v_cvt_pk_bf16_f32 v148, v148, v149
	v_cvt_pk_bf16_f32 v149, v150, v151
	v_cvt_pk_bf16_f32 v150, v154, v155
	v_cvt_pk_bf16_f32 v151, v152, v153
	global_store_dwordx4 v[144:145], v[148:151], off
	v_pk_fma_f32 v[152:153], v[2:3], s[56:57], v[114:115] op_sel_hi:[1,0,1]
	v_pk_fma_f32 v[154:155], v[0:1], s[56:57], v[112:113] op_sel_hi:[1,0,1]
	v_pk_fma_f32 v[150:151], v[6:7], s[56:57], v[122:123] op_sel_hi:[1,0,1]
	v_pk_fma_f32 v[148:149], v[4:5], s[56:57], v[120:121] op_sel_hi:[1,0,1]
	s_nop 0
	v_cvt_pk_bf16_f32 v148, v148, v149
	v_cvt_pk_bf16_f32 v149, v150, v151
	v_cvt_pk_bf16_f32 v150, v154, v155
	v_cvt_pk_bf16_f32 v151, v152, v153
	global_store_dwordx4 v[144:145], v[148:151], off offset:256
